# attention: waves whose 32 query rows cannot see the remaining diagonal-band key tiles skip the QK/softmax/PV work of those tiles (they still stage tiles and join the barriers)
# speedup vs baseline: 1.0072x; 1.0072x over previous
.LBB0_775:
	s_or_b64 exec, exec, s[4:5]
	s_and_b32 s60, s40, 0xff
	s_lshr_b32 s61, s60, 3
	s_sub_u32 s61, 15, s61
	s_and_b32 s64, s60, 7
	s_lshl_b32 s65, s44, 1
	s_lshl_b32 s45, s61, 2
	s_add_u32 s45, s45, 4
	s_sub_u32 s72, s45, 4
	v_lshrrev_b32_e32 v0, 6, v236
	s_nop 0
	v_readfirstlane_b32 s47, v0
	s_lshr_b32 s60, s47, 1
	s_add_u32 s78, s45, s60
	s_sub_u32 s78, s78, 3
	s_lshl_b32 s66, s64, 22
	s_lshr_b32 s67, s65, 1
	s_lshl_b32 s67, s67, 7
	s_add_u32 s48, s82, 0x9000000
	s_addc_u32 s49, s83, 0
	s_add_u32 s48, s48, s66
	s_addc_u32 s49, s49, 0
	s_add_u32 s48, s48, s67
	s_addc_u32 s49, s49, 0
	s_lshr_b32 s63, s65, 2
	s_lshl_b32 s63, s63, 8
	s_add_u32 s50, s82, 0xb000000
	s_addc_u32 s51, s83, 0
	s_add_u32 s50, s50, s66
	s_addc_u32 s51, s51, 0
	s_add_u32 s50, s50, s63
	s_addc_u32 s51, s51, 0
	s_lshl_b32 s63, s61, 8
	s_lshl_b32 s60, s47, 5
	s_add_u32 s63, s63, s60
	s_lshl_b32 s60, s63, 10
	s_add_u32 s54, s82, 0x7000000
	s_addc_u32 s55, s83, 0
	s_add_u32 s54, s54, s66
	s_addc_u32 s55, s55, 0
	s_add_u32 s54, s54, s60
	s_addc_u32 s55, s55, 0
	s_add_u32 s54, s54, s67
	s_addc_u32 s55, s55, 0
	s_lshl_b32 s60, s64, 12
	s_add_u32 s60, s60, s63
	s_lshl_b32 s60, s60, 11
	s_and_b32 s67, s65, 14
	s_lshl_b32 s67, s67, 7
	s_add_u32 s52, s82, 0x16000000
	s_addc_u32 s53, s83, 0
	s_add_u32 s52, s52, s60
	s_addc_u32 s53, s53, 0
	s_add_u32 s52, s52, s67
	s_addc_u32 s53, s53, 0
	v_and_b32_e32 v237, 63, v236
	v_lshrrev_b32_e32 v252, 5, v237
	v_and_b32_e32 v0, 31, v237
	s_lshl_b32 s60, s47, 4
	v_lshl_add_u32 v238, v237, 10, s60
	s_and_b32 s60, s47, 3
	s_lshl_b32 s60, s60, 14
	s_lshr_b32 s61, s47, 2
	s_lshl_b32 s61, s61, 6
	s_add_u32 s60, s60, s61
	v_lshrrev_b32_e32 v1, 2, v237
	v_lshlrev_b32_e32 v1, 10, v1
	v_and_b32_e32 v2, 3, v237
	v_lshl_or_b32 v1, v2, 4, v1
	v_add_u32_e32 v239, s60, v1
	v_lshlrev_b32_e32 v244, 10, v252
	v_lshl_or_b32 v244, v0, 4, v244
	v_bfe_u32 v1, v237, 4, 1
	v_lshlrev_b32_e32 v1, 5, v1
	v_lshl_or_b32 v1, v2, 3, v1
	v_bfe_u32 v2, v237, 2, 2
	v_lshl_or_b32 v2, v252, 2, v2
	v_lshl_or_b32 v1, v2, 6, v1
	v_add_u32_e32 v245, 24576, v1
	s_lshl_b32 s60, s47, 5
	v_add_u32_e32 v246, s60, v0
	s_lshl_b32 s60, s47, 8
	s_add_u32 s60, s60, 73728
	v_mov_b32_e32 v249, s60
	s_lshl_b32 s70, s47, 10
	s_add_u32 s71, s70, 24576
	s_mov_b64 s[74:75], s[48:49]
	s_mov_b64 s[76:77], s[50:51]
	s_mov_b32 s56, 0x4000
	s_mov_b32 s57, 0
	s_mov_b32 s58, 0x2000
	s_add_i32 m0, s57, s70
	s_nop 0
	global_load_lds_dwordx4 v238, s[74:75]
	s_add_u32 s74, s74, 0x10000
	s_addc_u32 s75, s75, 0
	s_lshl_b32 s60, s57, 1
	s_add_i32 s60, s60, s71
	s_mov_b32 m0, s60
	s_nop 0
	global_load_lds_dwordx4 v239, s[76:77]
	s_add_u32 s62, s76, 0x80
	s_addc_u32 s63, s77, 0
	s_add_i32 m0, s60, 0x2000
	s_nop 0
	global_load_lds_dwordx4 v239, s[62:63]
	s_add_u32 s76, s76, 0x10000
	s_addc_u32 s77, s77, 0
	s_add_i32 m0, s58, s70
	s_nop 0
	global_load_lds_dwordx4 v238, s[74:75]
	s_add_u32 s74, s74, 0x10000
	s_addc_u32 s75, s75, 0
	v_lshlrev_b32_e32 v1, 10, v0
	v_lshl_or_b32 v1, v252, 4, v1
	global_load_dwordx4 v[16:19], v1, s[54:55]
	global_load_dwordx4 v[20:23], v1, s[54:55] offset:32
	global_load_dwordx4 v[24:27], v1, s[54:55] offset:64
	global_load_dwordx4 v[28:31], v1, s[54:55] offset:96
	s_add_i32 m0, s56, s70
	s_nop 0
	global_load_lds_dwordx4 v238, s[74:75]
	s_add_u32 s74, s74, 0x10000
	s_addc_u32 s75, s75, 0
	v_mov_b32_e32 v248, 0
	v_mov_b32_e32 v247, 0
	v_mov_b32_e32 v160, 0
	v_mov_b32_e32 v161, 0
	v_mov_b32_e32 v162, 0
	v_mov_b32_e32 v163, 0
	v_mov_b32_e32 v164, 0
	v_mov_b32_e32 v165, 0
	v_mov_b32_e32 v166, 0
	v_mov_b32_e32 v167, 0
	v_mov_b32_e32 v168, 0
	v_mov_b32_e32 v169, 0
	v_mov_b32_e32 v170, 0
	v_mov_b32_e32 v171, 0
	v_mov_b32_e32 v172, 0
	v_mov_b32_e32 v173, 0
	v_mov_b32_e32 v174, 0
	v_mov_b32_e32 v175, 0
	v_mov_b32_e32 v32, 0
	v_mov_b32_e32 v33, 0
	v_mov_b32_e32 v34, 0
	v_mov_b32_e32 v35, 0
	v_mov_b32_e32 v36, 0
	v_mov_b32_e32 v37, 0
	v_mov_b32_e32 v38, 0
	v_mov_b32_e32 v39, 0
	v_mov_b32_e32 v40, 0
	v_mov_b32_e32 v41, 0
	v_mov_b32_e32 v42, 0
	v_mov_b32_e32 v43, 0
	v_mov_b32_e32 v44, 0
	v_mov_b32_e32 v45, 0
	v_mov_b32_e32 v46, 0
	v_mov_b32_e32 v47, 0
	v_mov_b32_e32 v48, 0
	v_mov_b32_e32 v49, 0
	v_mov_b32_e32 v50, 0
	v_mov_b32_e32 v51, 0
	v_mov_b32_e32 v52, 0
	v_mov_b32_e32 v53, 0
	v_mov_b32_e32 v54, 0
	v_mov_b32_e32 v55, 0
	v_mov_b32_e32 v56, 0
	v_mov_b32_e32 v57, 0
	v_mov_b32_e32 v58, 0
	v_mov_b32_e32 v59, 0
	v_mov_b32_e32 v60, 0
	v_mov_b32_e32 v61, 0
	v_mov_b32_e32 v62, 0
	v_mov_b32_e32 v63, 0
	v_mov_b32_e32 v64, 0
	v_mov_b32_e32 v65, 0
	v_mov_b32_e32 v66, 0
	v_mov_b32_e32 v67, 0
	v_mov_b32_e32 v68, 0
	v_mov_b32_e32 v69, 0
	v_mov_b32_e32 v70, 0
	v_mov_b32_e32 v71, 0
	v_mov_b32_e32 v72, 0
	v_mov_b32_e32 v73, 0
	v_mov_b32_e32 v74, 0
	v_mov_b32_e32 v75, 0
	v_mov_b32_e32 v76, 0
	v_mov_b32_e32 v77, 0
	v_mov_b32_e32 v78, 0
	v_mov_b32_e32 v79, 0
	v_mov_b32_e32 v80, 0
	v_mov_b32_e32 v81, 0
	v_mov_b32_e32 v82, 0
	v_mov_b32_e32 v83, 0
	v_mov_b32_e32 v84, 0
	v_mov_b32_e32 v85, 0
	v_mov_b32_e32 v86, 0
	v_mov_b32_e32 v87, 0
	v_mov_b32_e32 v88, 0
	v_mov_b32_e32 v89, 0
	v_mov_b32_e32 v90, 0
	v_mov_b32_e32 v91, 0
	v_mov_b32_e32 v92, 0
	v_mov_b32_e32 v93, 0
	v_mov_b32_e32 v94, 0
	v_mov_b32_e32 v95, 0
	s_mov_b32 s46, 0
	s_waitcnt vmcnt(8) lgkmcnt(0)
	s_barrier
	v_add_u32_e32 v250, s57, v244
	ds_read_b128 v[208:211], v250
	ds_read_b128 v[212:215], v250 offset:512
	ds_read_b128 v[216:219], v250 offset:2048
	ds_read_b128 v[220:223], v250 offset:2560
	ds_read_b128 v[224:227], v250 offset:4096
	ds_read_b128 v[228:231], v250 offset:4608
	ds_read_b128 v[232:235], v250 offset:6144
	ds_read_b128 v[240:243], v250 offset:6656
	s_waitcnt vmcnt(1) lgkmcnt(0)
	v_mfma_f32_32x32x16_bf16 v[96:111], v[208:211], v[16:19], v[160:175]
	v_mfma_f32_32x32x16_bf16 v[112:127], v[212:215], v[16:19], v[160:175]
	v_mfma_f32_32x32x16_bf16 v[96:111], v[216:219], v[20:23], v[96:111]
	v_mfma_f32_32x32x16_bf16 v[112:127], v[220:223], v[20:23], v[112:127]
	v_mfma_f32_32x32x16_bf16 v[96:111], v[224:227], v[24:27], v[96:111]
	v_mfma_f32_32x32x16_bf16 v[112:127], v[228:231], v[24:27], v[112:127]
	v_mfma_f32_32x32x16_bf16 v[96:111], v[232:235], v[28:31], v[96:111]
	v_mfma_f32_32x32x16_bf16 v[112:127], v[240:243], v[28:31], v[112:127]
	s_nop 7
	s_nop 7
	s_cmp_lt_u32 s46, s72
	s_cbranch_scc1 .Lat_nomask_229
	s_sub_u32 s60, s46, s72
	s_lshl_b32 s60, s60, 6
	v_lshl_add_u32 v0, v252, 2, s60
	v_sub_u32_e32 v0, v246, v0
	v_mov_b32_e32 v1, 0xff800000
	v_cmp_gt_i32_e64 s[60:61], 0, v0
	v_cmp_gt_i32_e64 s[62:63], 32, v0
	v_cmp_gt_i32_e64 s[64:65], 1, v0
	v_cmp_gt_i32_e64 s[66:67], 33, v0
	v_cndmask_b32_e64 v96, v96, v1, s[60:61]
	v_cmp_gt_i32_e64 s[60:61], 2, v0
	v_cndmask_b32_e64 v112, v112, v1, s[62:63]
	v_cmp_gt_i32_e64 s[62:63], 34, v0
	v_cndmask_b32_e64 v97, v97, v1, s[64:65]
	v_cmp_gt_i32_e64 s[64:65], 3, v0
	v_cndmask_b32_e64 v113, v113, v1, s[66:67]
	v_cmp_gt_i32_e64 s[66:67], 35, v0
	v_cndmask_b32_e64 v98, v98, v1, s[60:61]
	v_cmp_gt_i32_e64 s[60:61], 8, v0
	v_cndmask_b32_e64 v114, v114, v1, s[62:63]
	v_cmp_gt_i32_e64 s[62:63], 40, v0
	v_cndmask_b32_e64 v99, v99, v1, s[64:65]
	v_cmp_gt_i32_e64 s[64:65], 9, v0
	v_cndmask_b32_e64 v115, v115, v1, s[66:67]
	v_cmp_gt_i32_e64 s[66:67], 41, v0
	v_cndmask_b32_e64 v100, v100, v1, s[60:61]
	v_cmp_gt_i32_e64 s[60:61], 10, v0
	v_cndmask_b32_e64 v116, v116, v1, s[62:63]
	v_cmp_gt_i32_e64 s[62:63], 42, v0
	v_cndmask_b32_e64 v101, v101, v1, s[64:65]
	v_cmp_gt_i32_e64 s[64:65], 11, v0
	v_cndmask_b32_e64 v117, v117, v1, s[66:67]
	v_cmp_gt_i32_e64 s[66:67], 43, v0
	v_cndmask_b32_e64 v102, v102, v1, s[60:61]
	v_cmp_gt_i32_e64 s[60:61], 16, v0
	v_cndmask_b32_e64 v118, v118, v1, s[62:63]
	v_cmp_gt_i32_e64 s[62:63], 48, v0
	v_cndmask_b32_e64 v103, v103, v1, s[64:65]
	v_cmp_gt_i32_e64 s[64:65], 17, v0
	v_cndmask_b32_e64 v119, v119, v1, s[66:67]
	v_cmp_gt_i32_e64 s[66:67], 49, v0
	v_cndmask_b32_e64 v104, v104, v1, s[60:61]
	v_cmp_gt_i32_e64 s[60:61], 18, v0
	v_cndmask_b32_e64 v120, v120, v1, s[62:63]
	v_cmp_gt_i32_e64 s[62:63], 50, v0
	v_cndmask_b32_e64 v105, v105, v1, s[64:65]
	v_cmp_gt_i32_e64 s[64:65], 19, v0
	v_cndmask_b32_e64 v121, v121, v1, s[66:67]
	v_cmp_gt_i32_e64 s[66:67], 51, v0
	v_cndmask_b32_e64 v106, v106, v1, s[60:61]
	v_cmp_gt_i32_e64 s[60:61], 24, v0
	v_cndmask_b32_e64 v122, v122, v1, s[62:63]
	v_cmp_gt_i32_e64 s[62:63], 56, v0
	v_cndmask_b32_e64 v107, v107, v1, s[64:65]
	v_cmp_gt_i32_e64 s[64:65], 25, v0
	v_cndmask_b32_e64 v123, v123, v1, s[66:67]
	v_cmp_gt_i32_e64 s[66:67], 57, v0
	v_cndmask_b32_e64 v108, v108, v1, s[60:61]
	v_cmp_gt_i32_e64 s[60:61], 26, v0
	v_cndmask_b32_e64 v124, v124, v1, s[62:63]
	v_cmp_gt_i32_e64 s[62:63], 58, v0
	v_cndmask_b32_e64 v109, v109, v1, s[64:65]
	v_cmp_gt_i32_e64 s[64:65], 27, v0
	v_cndmask_b32_e64 v125, v125, v1, s[66:67]
	v_cmp_gt_i32_e64 s[66:67], 59, v0
	v_cndmask_b32_e64 v110, v110, v1, s[60:61]
	s_nop 1
	v_cndmask_b32_e64 v126, v126, v1, s[62:63]
	v_cndmask_b32_e64 v111, v111, v1, s[64:65]
	v_cndmask_b32_e64 v127, v127, v1, s[66:67]

.Lat_loop:
	s_cmp_ge_u32 s46, s45
	s_cbranch_scc1 .Lat_drain
	s_cmp_ge_u32 s46, s78
	s_cbranch_scc1 .Lat_lite_442
	s_lshl_b32 s60, s56, 1
	v_add_u32_e32 v250, s60, v245
	v_mfma_f32_32x32x16_bf16 v[128:143], v[208:211], v[16:19], v[160:175]
	v_add_f32_e32 v247, v247, v96
	v_add_f32_e32 v247, v247, v97
	v_add_f32_e32 v247, v247, v98
	v_add_f32_e32 v247, v247, v99
	v_cvt_pk_bf16_f32 v176, v96, v97
	v_cvt_pk_bf16_f32 v177, v98, v99
	v_mfma_f32_32x32x16_bf16 v[144:159], v[212:215], v[16:19], v[160:175]
	v_add_f32_e32 v247, v247, v100
	v_add_f32_e32 v247, v247, v101
	v_add_f32_e32 v247, v247, v102
	v_add_f32_e32 v247, v247, v103
	v_cvt_pk_bf16_f32 v178, v100, v101
	v_cvt_pk_bf16_f32 v179, v102, v103
	v_mfma_f32_32x32x16_bf16 v[128:143], v[216:219], v[20:23], v[128:143]
	v_add_f32_e32 v247, v247, v104
	v_add_f32_e32 v247, v247, v105
	v_add_f32_e32 v247, v247, v106
	v_add_f32_e32 v247, v247, v107
	v_cvt_pk_bf16_f32 v180, v104, v105
	v_cvt_pk_bf16_f32 v181, v106, v107
	v_mfma_f32_32x32x16_bf16 v[144:159], v[220:223], v[20:23], v[144:159]
	v_add_f32_e32 v247, v247, v108
	v_add_f32_e32 v247, v247, v109
	v_add_f32_e32 v247, v247, v110
	v_add_f32_e32 v247, v247, v111
	v_cvt_pk_bf16_f32 v182, v108, v109
	v_cvt_pk_bf16_f32 v183, v110, v111
	v_mfma_f32_32x32x16_bf16 v[128:143], v[224:227], v[24:27], v[128:143]
	v_add_f32_e32 v247, v247, v112
	v_add_f32_e32 v247, v247, v113
	v_add_f32_e32 v247, v247, v114
	v_add_f32_e32 v247, v247, v115
	v_cvt_pk_bf16_f32 v184, v112, v113
	v_cvt_pk_bf16_f32 v185, v114, v115
	v_mfma_f32_32x32x16_bf16 v[144:159], v[228:231], v[24:27], v[144:159]
	v_add_f32_e32 v247, v247, v116
	v_add_f32_e32 v247, v247, v117
	v_add_f32_e32 v247, v247, v118
	v_add_f32_e32 v247, v247, v119
	v_cvt_pk_bf16_f32 v186, v116, v117
	v_cvt_pk_bf16_f32 v187, v118, v119
	v_mfma_f32_32x32x16_bf16 v[128:143], v[232:235], v[28:31], v[128:143]
	v_add_f32_e32 v247, v247, v120
	v_add_f32_e32 v247, v247, v121
	v_add_f32_e32 v247, v247, v122
	v_add_f32_e32 v247, v247, v123
	v_cvt_pk_bf16_f32 v188, v120, v121
	v_cvt_pk_bf16_f32 v189, v122, v123
	ds_read_b64_tr_b16 v[192:193], v250 offset:0
	ds_read_b64_tr_b16 v[194:195], v250 offset:512
	v_mfma_f32_32x32x16_bf16 v[144:159], v[240:243], v[28:31], v[144:159]
	v_add_f32_e32 v247, v247, v124
	v_add_f32_e32 v247, v247, v125
	v_add_f32_e32 v247, v247, v126
	v_add_f32_e32 v247, v247, v127
	v_cvt_pk_bf16_f32 v190, v124, v125
	v_cvt_pk_bf16_f32 v191, v126, v127
	ds_read_b64_tr_b16 v[196:197], v250 offset:4096
	ds_read_b64_tr_b16 v[198:199], v250 offset:4608
	s_add_i32 m0, s57, s70
	s_nop 0
	global_load_lds_dwordx4 v238, s[74:75]
	s_add_u32 s74, s74, 0x10000
	s_addc_u32 s75, s75, 0
	s_lshl_b32 s60, s58, 1
	s_add_i32 s60, s60, s71
	s_mov_b32 m0, s60
	s_nop 0
	global_load_lds_dwordx4 v239, s[76:77]
	s_add_u32 s62, s76, 0x80
	s_addc_u32 s63, s77, 0
	s_add_i32 m0, s60, 0x2000
	s_nop 0
	global_load_lds_dwordx4 v239, s[62:63]
	s_add_u32 s76, s76, 0x10000
	s_addc_u32 s77, s77, 0
	s_cmp_lt_u32 s46, s72
	s_cbranch_scc1 .Lat_nomask_525
	s_sub_u32 s60, s46, s72
	s_lshl_b32 s60, s60, 6
	v_lshl_add_u32 v0, v252, 2, s60
	v_sub_u32_e32 v0, v246, v0
	v_mov_b32_e32 v1, 0xff800000
	v_cmp_gt_i32_e64 s[60:61], 0, v0
	v_cmp_gt_i32_e64 s[62:63], 32, v0
	v_cmp_gt_i32_e64 s[64:65], 1, v0
	v_cmp_gt_i32_e64 s[66:67], 33, v0
	v_cndmask_b32_e64 v128, v128, v1, s[60:61]
	v_cmp_gt_i32_e64 s[60:61], 2, v0
	v_cndmask_b32_e64 v144, v144, v1, s[62:63]
	v_cmp_gt_i32_e64 s[62:63], 34, v0
	v_cndmask_b32_e64 v129, v129, v1, s[64:65]
	v_cmp_gt_i32_e64 s[64:65], 3, v0
	v_cndmask_b32_e64 v145, v145, v1, s[66:67]
	v_cmp_gt_i32_e64 s[66:67], 35, v0
	v_cndmask_b32_e64 v130, v130, v1, s[60:61]
	v_cmp_gt_i32_e64 s[60:61], 8, v0
	v_cndmask_b32_e64 v146, v146, v1, s[62:63]
	v_cmp_gt_i32_e64 s[62:63], 40, v0
	v_cndmask_b32_e64 v131, v131, v1, s[64:65]
	v_cmp_gt_i32_e64 s[64:65], 9, v0
	v_cndmask_b32_e64 v147, v147, v1, s[66:67]
	v_cmp_gt_i32_e64 s[66:67], 41, v0
	v_cndmask_b32_e64 v132, v132, v1, s[60:61]
	v_cmp_gt_i32_e64 s[60:61], 10, v0
	v_cndmask_b32_e64 v148, v148, v1, s[62:63]
	v_cmp_gt_i32_e64 s[62:63], 42, v0
	v_cndmask_b32_e64 v133, v133, v1, s[64:65]
	v_cmp_gt_i32_e64 s[64:65], 11, v0
	v_cndmask_b32_e64 v149, v149, v1, s[66:67]
	v_cmp_gt_i32_e64 s[66:67], 43, v0
	v_cndmask_b32_e64 v134, v134, v1, s[60:61]
	v_cmp_gt_i32_e64 s[60:61], 16, v0
	v_cndmask_b32_e64 v150, v150, v1, s[62:63]
	v_cmp_gt_i32_e64 s[62:63], 48, v0
	v_cndmask_b32_e64 v135, v135, v1, s[64:65]
	v_cmp_gt_i32_e64 s[64:65], 17, v0
	v_cndmask_b32_e64 v151, v151, v1, s[66:67]
	v_cmp_gt_i32_e64 s[66:67], 49, v0
	v_cndmask_b32_e64 v136, v136, v1, s[60:61]
	v_cmp_gt_i32_e64 s[60:61], 18, v0
	v_cndmask_b32_e64 v152, v152, v1, s[62:63]
	v_cmp_gt_i32_e64 s[62:63], 50, v0
	v_cndmask_b32_e64 v137, v137, v1, s[64:65]
	v_cmp_gt_i32_e64 s[64:65], 19, v0
	v_cndmask_b32_e64 v153, v153, v1, s[66:67]
	v_cmp_gt_i32_e64 s[66:67], 51, v0
	v_cndmask_b32_e64 v138, v138, v1, s[60:61]
	v_cmp_gt_i32_e64 s[60:61], 24, v0
	v_cndmask_b32_e64 v154, v154, v1, s[62:63]
	v_cmp_gt_i32_e64 s[62:63], 56, v0
	v_cndmask_b32_e64 v139, v139, v1, s[64:65]
	v_cmp_gt_i32_e64 s[64:65], 25, v0
	v_cndmask_b32_e64 v155, v155, v1, s[66:67]
	v_cmp_gt_i32_e64 s[66:67], 57, v0
	v_cndmask_b32_e64 v140, v140, v1, s[60:61]
	v_cmp_gt_i32_e64 s[60:61], 26, v0
	v_cndmask_b32_e64 v156, v156, v1, s[62:63]
	v_cmp_gt_i32_e64 s[62:63], 58, v0
	v_cndmask_b32_e64 v141, v141, v1, s[64:65]
	v_cmp_gt_i32_e64 s[64:65], 27, v0
	v_cndmask_b32_e64 v157, v157, v1, s[66:67]
	v_cmp_gt_i32_e64 s[66:67], 59, v0
	v_cndmask_b32_e64 v142, v142, v1, s[60:61]
	s_nop 1
	v_cndmask_b32_e64 v158, v158, v1, s[62:63]
	v_cndmask_b32_e64 v143, v143, v1, s[64:65]
	v_cndmask_b32_e64 v159, v159, v1, s[66:67]

.Lat_next_442:
	s_cmp_ge_u32 s46, s45
	s_cbranch_scc1 .Lat_drain
	s_cmp_ge_u32 s46, s78
	s_cbranch_scc1 .Lat_lite_861
	s_lshl_b32 s60, s56, 1
	v_add_u32_e32 v250, s60, v245
	v_mfma_f32_32x32x16_bf16 v[96:111], v[208:211], v[16:19], v[160:175]
	v_add_f32_e32 v247, v247, v128
	v_add_f32_e32 v247, v247, v129
	v_add_f32_e32 v247, v247, v130
	v_add_f32_e32 v247, v247, v131
	v_cvt_pk_bf16_f32 v176, v128, v129
	v_cvt_pk_bf16_f32 v177, v130, v131
	v_mfma_f32_32x32x16_bf16 v[112:127], v[212:215], v[16:19], v[160:175]
	v_add_f32_e32 v247, v247, v132
	v_add_f32_e32 v247, v247, v133
	v_add_f32_e32 v247, v247, v134
	v_add_f32_e32 v247, v247, v135
	v_cvt_pk_bf16_f32 v178, v132, v133
	v_cvt_pk_bf16_f32 v179, v134, v135
	v_mfma_f32_32x32x16_bf16 v[96:111], v[216:219], v[20:23], v[96:111]
	v_add_f32_e32 v247, v247, v136
	v_add_f32_e32 v247, v247, v137
	v_add_f32_e32 v247, v247, v138
	v_add_f32_e32 v247, v247, v139
	v_cvt_pk_bf16_f32 v180, v136, v137
	v_cvt_pk_bf16_f32 v181, v138, v139
	v_mfma_f32_32x32x16_bf16 v[112:127], v[220:223], v[20:23], v[112:127]
	v_add_f32_e32 v247, v247, v140
	v_add_f32_e32 v247, v247, v141
	v_add_f32_e32 v247, v247, v142
	v_add_f32_e32 v247, v247, v143
	v_cvt_pk_bf16_f32 v182, v140, v141
	v_cvt_pk_bf16_f32 v183, v142, v143
	v_mfma_f32_32x32x16_bf16 v[96:111], v[224:227], v[24:27], v[96:111]
	v_add_f32_e32 v247, v247, v144
	v_add_f32_e32 v247, v247, v145
	v_add_f32_e32 v247, v247, v146
	v_add_f32_e32 v247, v247, v147
	v_cvt_pk_bf16_f32 v184, v144, v145
	v_cvt_pk_bf16_f32 v185, v146, v147
	v_mfma_f32_32x32x16_bf16 v[112:127], v[228:231], v[24:27], v[112:127]
	v_add_f32_e32 v247, v247, v148
	v_add_f32_e32 v247, v247, v149
	v_add_f32_e32 v247, v247, v150
	v_add_f32_e32 v247, v247, v151
	v_cvt_pk_bf16_f32 v186, v148, v149
	v_cvt_pk_bf16_f32 v187, v150, v151
	v_mfma_f32_32x32x16_bf16 v[96:111], v[232:235], v[28:31], v[96:111]
	v_add_f32_e32 v247, v247, v152
	v_add_f32_e32 v247, v247, v153
	v_add_f32_e32 v247, v247, v154
	v_add_f32_e32 v247, v247, v155
	v_cvt_pk_bf16_f32 v188, v152, v153
	v_cvt_pk_bf16_f32 v189, v154, v155
	ds_read_b64_tr_b16 v[192:193], v250 offset:0
	ds_read_b64_tr_b16 v[194:195], v250 offset:512
	v_mfma_f32_32x32x16_bf16 v[112:127], v[240:243], v[28:31], v[112:127]
	v_add_f32_e32 v247, v247, v156
	v_add_f32_e32 v247, v247, v157
	v_add_f32_e32 v247, v247, v158
	v_add_f32_e32 v247, v247, v159
	v_cvt_pk_bf16_f32 v190, v156, v157
	v_cvt_pk_bf16_f32 v191, v158, v159
	ds_read_b64_tr_b16 v[196:197], v250 offset:4096
	ds_read_b64_tr_b16 v[198:199], v250 offset:4608
	s_add_i32 m0, s57, s70
	s_nop 0
	global_load_lds_dwordx4 v238, s[74:75]
	s_add_u32 s74, s74, 0x10000
	s_addc_u32 s75, s75, 0
	s_lshl_b32 s60, s58, 1
	s_add_i32 s60, s60, s71
	s_mov_b32 m0, s60
	s_nop 0
	global_load_lds_dwordx4 v239, s[76:77]
	s_add_u32 s62, s76, 0x80
	s_addc_u32 s63, s77, 0
	s_add_i32 m0, s60, 0x2000
	s_nop 0
	global_load_lds_dwordx4 v239, s[62:63]
	s_add_u32 s76, s76, 0x10000
	s_addc_u32 s77, s77, 0
	s_cmp_lt_u32 s46, s72
	s_cbranch_scc1 .Lat_nomask_944
	s_sub_u32 s60, s46, s72
	s_lshl_b32 s60, s60, 6
	v_lshl_add_u32 v0, v252, 2, s60
	v_sub_u32_e32 v0, v246, v0
	v_mov_b32_e32 v1, 0xff800000
	v_cmp_gt_i32_e64 s[60:61], 0, v0
	v_cmp_gt_i32_e64 s[62:63], 32, v0
	v_cmp_gt_i32_e64 s[64:65], 1, v0
	v_cmp_gt_i32_e64 s[66:67], 33, v0
	v_cndmask_b32_e64 v96, v96, v1, s[60:61]
	v_cmp_gt_i32_e64 s[60:61], 2, v0
	v_cndmask_b32_e64 v112, v112, v1, s[62:63]
	v_cmp_gt_i32_e64 s[62:63], 34, v0
	v_cndmask_b32_e64 v97, v97, v1, s[64:65]
	v_cmp_gt_i32_e64 s[64:65], 3, v0
	v_cndmask_b32_e64 v113, v113, v1, s[66:67]
	v_cmp_gt_i32_e64 s[66:67], 35, v0
	v_cndmask_b32_e64 v98, v98, v1, s[60:61]
	v_cmp_gt_i32_e64 s[60:61], 8, v0
	v_cndmask_b32_e64 v114, v114, v1, s[62:63]
	v_cmp_gt_i32_e64 s[62:63], 40, v0
	v_cndmask_b32_e64 v99, v99, v1, s[64:65]
	v_cmp_gt_i32_e64 s[64:65], 9, v0
	v_cndmask_b32_e64 v115, v115, v1, s[66:67]
	v_cmp_gt_i32_e64 s[66:67], 41, v0
	v_cndmask_b32_e64 v100, v100, v1, s[60:61]
	v_cmp_gt_i32_e64 s[60:61], 10, v0
	v_cndmask_b32_e64 v116, v116, v1, s[62:63]
	v_cmp_gt_i32_e64 s[62:63], 42, v0
	v_cndmask_b32_e64 v101, v101, v1, s[64:65]
	v_cmp_gt_i32_e64 s[64:65], 11, v0
	v_cndmask_b32_e64 v117, v117, v1, s[66:67]
	v_cmp_gt_i32_e64 s[66:67], 43, v0
	v_cndmask_b32_e64 v102, v102, v1, s[60:61]
	v_cmp_gt_i32_e64 s[60:61], 16, v0
	v_cndmask_b32_e64 v118, v118, v1, s[62:63]
	v_cmp_gt_i32_e64 s[62:63], 48, v0
	v_cndmask_b32_e64 v103, v103, v1, s[64:65]
	v_cmp_gt_i32_e64 s[64:65], 17, v0
	v_cndmask_b32_e64 v119, v119, v1, s[66:67]
	v_cmp_gt_i32_e64 s[66:67], 49, v0
	v_cndmask_b32_e64 v104, v104, v1, s[60:61]
	v_cmp_gt_i32_e64 s[60:61], 18, v0
	v_cndmask_b32_e64 v120, v120, v1, s[62:63]
	v_cmp_gt_i32_e64 s[62:63], 50, v0
	v_cndmask_b32_e64 v105, v105, v1, s[64:65]
	v_cmp_gt_i32_e64 s[64:65], 19, v0
	v_cndmask_b32_e64 v121, v121, v1, s[66:67]
	v_cmp_gt_i32_e64 s[66:67], 51, v0
	v_cndmask_b32_e64 v106, v106, v1, s[60:61]
	v_cmp_gt_i32_e64 s[60:61], 24, v0
	v_cndmask_b32_e64 v122, v122, v1, s[62:63]
	v_cmp_gt_i32_e64 s[62:63], 56, v0
	v_cndmask_b32_e64 v107, v107, v1, s[64:65]
	v_cmp_gt_i32_e64 s[64:65], 25, v0
	v_cndmask_b32_e64 v123, v123, v1, s[66:67]
	v_cmp_gt_i32_e64 s[66:67], 57, v0
	v_cndmask_b32_e64 v108, v108, v1, s[60:61]
	v_cmp_gt_i32_e64 s[60:61], 26, v0
	v_cndmask_b32_e64 v124, v124, v1, s[62:63]
	v_cmp_gt_i32_e64 s[62:63], 58, v0
	v_cndmask_b32_e64 v109, v109, v1, s[64:65]
	v_cmp_gt_i32_e64 s[64:65], 27, v0
	v_cndmask_b32_e64 v125, v125, v1, s[66:67]
	v_cmp_gt_i32_e64 s[66:67], 59, v0
	v_cndmask_b32_e64 v110, v110, v1, s[60:61]
	s_nop 1
	v_cndmask_b32_e64 v126, v126, v1, s[62:63]
	v_cndmask_b32_e64 v111, v111, v1, s[64:65]
	v_cndmask_b32_e64 v127, v127, v1, s[66:67]

.Lat_next_861:
	s_cmp_lt_u32 s46, s45
	s_cbranch_scc1 .Lat_loop
	s_branch .Lat_drain
.Lat_lite_442:
	s_cmp_eq_u32 s46, s78
	s_cbranch_scc0 .Lat_lite2_442
	v_add_f32_e32 v247, v247, v96
	v_add_f32_e32 v247, v247, v97
	v_add_f32_e32 v247, v247, v98
	v_add_f32_e32 v247, v247, v99
	v_cvt_pk_bf16_f32 v176, v96, v97
	v_cvt_pk_bf16_f32 v177, v98, v99
	v_add_f32_e32 v247, v247, v100
	v_add_f32_e32 v247, v247, v101
	v_add_f32_e32 v247, v247, v102
	v_add_f32_e32 v247, v247, v103
	v_cvt_pk_bf16_f32 v178, v100, v101
	v_cvt_pk_bf16_f32 v179, v102, v103
	v_add_f32_e32 v247, v247, v104
	v_add_f32_e32 v247, v247, v105
	v_add_f32_e32 v247, v247, v106
	v_add_f32_e32 v247, v247, v107
	v_cvt_pk_bf16_f32 v180, v104, v105
	v_cvt_pk_bf16_f32 v181, v106, v107
	v_add_f32_e32 v247, v247, v108
	v_add_f32_e32 v247, v247, v109
	v_add_f32_e32 v247, v247, v110
	v_add_f32_e32 v247, v247, v111
	v_cvt_pk_bf16_f32 v182, v108, v109
	v_cvt_pk_bf16_f32 v183, v110, v111
	v_add_f32_e32 v247, v247, v112
	v_add_f32_e32 v247, v247, v113
	v_add_f32_e32 v247, v247, v114
	v_add_f32_e32 v247, v247, v115
	v_cvt_pk_bf16_f32 v184, v112, v113
	v_cvt_pk_bf16_f32 v185, v114, v115
	v_add_f32_e32 v247, v247, v116
	v_add_f32_e32 v247, v247, v117
	v_add_f32_e32 v247, v247, v118
	v_add_f32_e32 v247, v247, v119
	v_cvt_pk_bf16_f32 v186, v116, v117
	v_cvt_pk_bf16_f32 v187, v118, v119
	v_add_f32_e32 v247, v247, v120
	v_add_f32_e32 v247, v247, v121
	v_add_f32_e32 v247, v247, v122
	v_add_f32_e32 v247, v247, v123
	v_cvt_pk_bf16_f32 v188, v120, v121
	v_cvt_pk_bf16_f32 v189, v122, v123
	v_add_f32_e32 v247, v247, v124
	v_add_f32_e32 v247, v247, v125
	v_add_f32_e32 v247, v247, v126
	v_add_f32_e32 v247, v247, v127
	v_cvt_pk_bf16_f32 v190, v124, v125
	v_cvt_pk_bf16_f32 v191, v126, v127
	s_lshl_b32 s60, s56, 1
	v_add_u32_e32 v250, s60, v245
	ds_read_b64_tr_b16 v[192:193], v250 offset:0
	ds_read_b64_tr_b16 v[194:195], v250 offset:512
	ds_read_b64_tr_b16 v[196:197], v250 offset:4096
	ds_read_b64_tr_b16 v[198:199], v250 offset:4608
	ds_read_b64_tr_b16 v[200:201], v250 offset:8192
	ds_read_b64_tr_b16 v[202:203], v250 offset:8704
	ds_read_b64_tr_b16 v[204:205], v250 offset:12288
	ds_read_b64_tr_b16 v[206:207], v250 offset:12800
	s_waitcnt lgkmcnt(6)
	v_mfma_f32_32x32x16_bf16 v[32:47], v[176:179], v[192:195], v[32:47]
	ds_read_b64_tr_b16 v[192:193], v250 offset:1024
	ds_read_b64_tr_b16 v[194:195], v250 offset:1536
	s_waitcnt lgkmcnt(6)
	v_mfma_f32_32x32x16_bf16 v[48:63], v[176:179], v[196:199], v[48:63]
	ds_read_b64_tr_b16 v[196:197], v250 offset:5120
	ds_read_b64_tr_b16 v[198:199], v250 offset:5632
	s_waitcnt lgkmcnt(6)
	v_mfma_f32_32x32x16_bf16 v[64:79], v[176:179], v[200:203], v[64:79]
	ds_read_b64_tr_b16 v[200:201], v250 offset:9216
	ds_read_b64_tr_b16 v[202:203], v250 offset:9728
	s_waitcnt lgkmcnt(6)
	v_mfma_f32_32x32x16_bf16 v[80:95], v[176:179], v[204:207], v[80:95]
	ds_read_b64_tr_b16 v[204:205], v250 offset:13312
	ds_read_b64_tr_b16 v[206:207], v250 offset:13824
	s_waitcnt lgkmcnt(6)
	v_mfma_f32_32x32x16_bf16 v[32:47], v[180:183], v[192:195], v[32:47]
	ds_read_b64_tr_b16 v[192:193], v250 offset:2048
	ds_read_b64_tr_b16 v[194:195], v250 offset:2560
	s_waitcnt lgkmcnt(6)
	v_mfma_f32_32x32x16_bf16 v[48:63], v[180:183], v[196:199], v[48:63]
	ds_read_b64_tr_b16 v[196:197], v250 offset:6144
	ds_read_b64_tr_b16 v[198:199], v250 offset:6656
	s_waitcnt lgkmcnt(6)
	v_mfma_f32_32x32x16_bf16 v[64:79], v[180:183], v[200:203], v[64:79]
	ds_read_b64_tr_b16 v[200:201], v250 offset:10240
	ds_read_b64_tr_b16 v[202:203], v250 offset:10752
	s_waitcnt lgkmcnt(6)
	v_mfma_f32_32x32x16_bf16 v[80:95], v[180:183], v[204:207], v[80:95]
	ds_read_b64_tr_b16 v[204:205], v250 offset:14336
	ds_read_b64_tr_b16 v[206:207], v250 offset:14848
	s_waitcnt lgkmcnt(6)
	v_mfma_f32_32x32x16_bf16 v[32:47], v[184:187], v[192:195], v[32:47]
	ds_read_b64_tr_b16 v[192:193], v250 offset:3072
	ds_read_b64_tr_b16 v[194:195], v250 offset:3584
	s_waitcnt lgkmcnt(6)
	v_mfma_f32_32x32x16_bf16 v[48:63], v[184:187], v[196:199], v[48:63]
	ds_read_b64_tr_b16 v[196:197], v250 offset:7168
	ds_read_b64_tr_b16 v[198:199], v250 offset:7680
	s_waitcnt lgkmcnt(6)
	v_mfma_f32_32x32x16_bf16 v[64:79], v[184:187], v[200:203], v[64:79]
	ds_read_b64_tr_b16 v[200:201], v250 offset:11264
	ds_read_b64_tr_b16 v[202:203], v250 offset:11776
	s_waitcnt lgkmcnt(6)
	v_mfma_f32_32x32x16_bf16 v[80:95], v[184:187], v[204:207], v[80:95]
	ds_read_b64_tr_b16 v[204:205], v250 offset:15360
	ds_read_b64_tr_b16 v[206:207], v250 offset:15872
	s_waitcnt lgkmcnt(6)
	v_mfma_f32_32x32x16_bf16 v[32:47], v[188:191], v[192:195], v[32:47]
	s_waitcnt lgkmcnt(4)
	v_mfma_f32_32x32x16_bf16 v[48:63], v[188:191], v[196:199], v[48:63]
	s_waitcnt lgkmcnt(2)
	v_mfma_f32_32x32x16_bf16 v[64:79], v[188:191], v[200:203], v[64:79]
	s_waitcnt lgkmcnt(0)
	v_mfma_f32_32x32x16_bf16 v[80:95], v[188:191], v[204:207], v[80:95]
.Lat_lite2_442:
	s_add_i32 m0, s57, s70
	s_nop 0
	global_load_lds_dwordx4 v238, s[74:75]
	s_add_u32 s74, s74, 0x10000
	s_addc_u32 s75, s75, 0
	s_lshl_b32 s60, s58, 1
	s_add_i32 s60, s60, s71
	s_mov_b32 m0, s60
	s_nop 0
	global_load_lds_dwordx4 v239, s[76:77]
	s_add_u32 s62, s76, 0x80
	s_addc_u32 s63, s77, 0
	s_add_i32 m0, s60, 0x2000
	s_nop 0
	global_load_lds_dwordx4 v239, s[62:63]
	s_add_u32 s76, s76, 0x10000
	s_addc_u32 s77, s77, 0
	s_waitcnt vmcnt(3) lgkmcnt(0)
	s_barrier
	s_mov_b32 s67, s56
	s_mov_b32 s56, s57
	s_mov_b32 s57, s58
	s_mov_b32 s58, s67
	s_add_u32 s46, s46, 1
	s_branch .Lat_next_442
.Lat_lite_861:
	s_cmp_eq_u32 s46, s78
	s_cbranch_scc0 .Lat_lite2_861
	v_add_f32_e32 v247, v247, v128
	v_add_f32_e32 v247, v247, v129
	v_add_f32_e32 v247, v247, v130
	v_add_f32_e32 v247, v247, v131
	v_cvt_pk_bf16_f32 v176, v128, v129
	v_cvt_pk_bf16_f32 v177, v130, v131
	v_add_f32_e32 v247, v247, v132
	v_add_f32_e32 v247, v247, v133
	v_add_f32_e32 v247, v247, v134
	v_add_f32_e32 v247, v247, v135
	v_cvt_pk_bf16_f32 v178, v132, v133
	v_cvt_pk_bf16_f32 v179, v134, v135
	v_add_f32_e32 v247, v247, v136
	v_add_f32_e32 v247, v247, v137
	v_add_f32_e32 v247, v247, v138
	v_add_f32_e32 v247, v247, v139
	v_cvt_pk_bf16_f32 v180, v136, v137
	v_cvt_pk_bf16_f32 v181, v138, v139
	v_add_f32_e32 v247, v247, v140
	v_add_f32_e32 v247, v247, v141
	v_add_f32_e32 v247, v247, v142
	v_add_f32_e32 v247, v247, v143
	v_cvt_pk_bf16_f32 v182, v140, v141
	v_cvt_pk_bf16_f32 v183, v142, v143
	v_add_f32_e32 v247, v247, v144
	v_add_f32_e32 v247, v247, v145
	v_add_f32_e32 v247, v247, v146
	v_add_f32_e32 v247, v247, v147
	v_cvt_pk_bf16_f32 v184, v144, v145
	v_cvt_pk_bf16_f32 v185, v146, v147
	v_add_f32_e32 v247, v247, v148
	v_add_f32_e32 v247, v247, v149
	v_add_f32_e32 v247, v247, v150
	v_add_f32_e32 v247, v247, v151
	v_cvt_pk_bf16_f32 v186, v148, v149
	v_cvt_pk_bf16_f32 v187, v150, v151
	v_add_f32_e32 v247, v247, v152
	v_add_f32_e32 v247, v247, v153
	v_add_f32_e32 v247, v247, v154
	v_add_f32_e32 v247, v247, v155
	v_cvt_pk_bf16_f32 v188, v152, v153
	v_cvt_pk_bf16_f32 v189, v154, v155
	v_add_f32_e32 v247, v247, v156
	v_add_f32_e32 v247, v247, v157
	v_add_f32_e32 v247, v247, v158
	v_add_f32_e32 v247, v247, v159
	v_cvt_pk_bf16_f32 v190, v156, v157
	v_cvt_pk_bf16_f32 v191, v158, v159
	s_lshl_b32 s60, s56, 1
	v_add_u32_e32 v250, s60, v245
	ds_read_b64_tr_b16 v[192:193], v250 offset:0
	ds_read_b64_tr_b16 v[194:195], v250 offset:512
	ds_read_b64_tr_b16 v[196:197], v250 offset:4096
	ds_read_b64_tr_b16 v[198:199], v250 offset:4608
	ds_read_b64_tr_b16 v[200:201], v250 offset:8192
	ds_read_b64_tr_b16 v[202:203], v250 offset:8704
	ds_read_b64_tr_b16 v[204:205], v250 offset:12288
	ds_read_b64_tr_b16 v[206:207], v250 offset:12800
	s_waitcnt lgkmcnt(6)
	v_mfma_f32_32x32x16_bf16 v[32:47], v[176:179], v[192:195], v[32:47]
	ds_read_b64_tr_b16 v[192:193], v250 offset:1024
	ds_read_b64_tr_b16 v[194:195], v250 offset:1536
	s_waitcnt lgkmcnt(6)
	v_mfma_f32_32x32x16_bf16 v[48:63], v[176:179], v[196:199], v[48:63]
	ds_read_b64_tr_b16 v[196:197], v250 offset:5120
	ds_read_b64_tr_b16 v[198:199], v250 offset:5632
	s_waitcnt lgkmcnt(6)
	v_mfma_f32_32x32x16_bf16 v[64:79], v[176:179], v[200:203], v[64:79]
	ds_read_b64_tr_b16 v[200:201], v250 offset:9216
	ds_read_b64_tr_b16 v[202:203], v250 offset:9728
	s_waitcnt lgkmcnt(6)
	v_mfma_f32_32x32x16_bf16 v[80:95], v[176:179], v[204:207], v[80:95]
	ds_read_b64_tr_b16 v[204:205], v250 offset:13312
	ds_read_b64_tr_b16 v[206:207], v250 offset:13824
	s_waitcnt lgkmcnt(6)
	v_mfma_f32_32x32x16_bf16 v[32:47], v[180:183], v[192:195], v[32:47]
	ds_read_b64_tr_b16 v[192:193], v250 offset:2048
	ds_read_b64_tr_b16 v[194:195], v250 offset:2560
	s_waitcnt lgkmcnt(6)
	v_mfma_f32_32x32x16_bf16 v[48:63], v[180:183], v[196:199], v[48:63]
	ds_read_b64_tr_b16 v[196:197], v250 offset:6144
	ds_read_b64_tr_b16 v[198:199], v250 offset:6656
	s_waitcnt lgkmcnt(6)
	v_mfma_f32_32x32x16_bf16 v[64:79], v[180:183], v[200:203], v[64:79]
	ds_read_b64_tr_b16 v[200:201], v250 offset:10240
	ds_read_b64_tr_b16 v[202:203], v250 offset:10752
	s_waitcnt lgkmcnt(6)
	v_mfma_f32_32x32x16_bf16 v[80:95], v[180:183], v[204:207], v[80:95]
	ds_read_b64_tr_b16 v[204:205], v250 offset:14336
	ds_read_b64_tr_b16 v[206:207], v250 offset:14848
	s_waitcnt lgkmcnt(6)
	v_mfma_f32_32x32x16_bf16 v[32:47], v[184:187], v[192:195], v[32:47]
	ds_read_b64_tr_b16 v[192:193], v250 offset:3072
	ds_read_b64_tr_b16 v[194:195], v250 offset:3584
	s_waitcnt lgkmcnt(6)
	v_mfma_f32_32x32x16_bf16 v[48:63], v[184:187], v[196:199], v[48:63]
	ds_read_b64_tr_b16 v[196:197], v250 offset:7168
	ds_read_b64_tr_b16 v[198:199], v250 offset:7680
	s_waitcnt lgkmcnt(6)
	v_mfma_f32_32x32x16_bf16 v[64:79], v[184:187], v[200:203], v[64:79]
	ds_read_b64_tr_b16 v[200:201], v250 offset:11264
	ds_read_b64_tr_b16 v[202:203], v250 offset:11776
	s_waitcnt lgkmcnt(6)
	v_mfma_f32_32x32x16_bf16 v[80:95], v[184:187], v[204:207], v[80:95]
	ds_read_b64_tr_b16 v[204:205], v250 offset:15360
	ds_read_b64_tr_b16 v[206:207], v250 offset:15872
	s_waitcnt lgkmcnt(6)
	v_mfma_f32_32x32x16_bf16 v[32:47], v[188:191], v[192:195], v[32:47]
	s_waitcnt lgkmcnt(4)
	v_mfma_f32_32x32x16_bf16 v[48:63], v[188:191], v[196:199], v[48:63]
	s_waitcnt lgkmcnt(2)
	v_mfma_f32_32x32x16_bf16 v[64:79], v[188:191], v[200:203], v[64:79]
	s_waitcnt lgkmcnt(0)
	v_mfma_f32_32x32x16_bf16 v[80:95], v[188:191], v[204:207], v[80:95]

.Lat_drain:
	s_cmp_lt_u32 s78, s45
	s_cbranch_scc1 .Lat_epi
	v_add_f32_e32 v247, v247, v128
	v_add_f32_e32 v247, v247, v129
	v_add_f32_e32 v247, v247, v130
	v_add_f32_e32 v247, v247, v131
	v_cvt_pk_bf16_f32 v176, v128, v129
	v_cvt_pk_bf16_f32 v177, v130, v131
	v_add_f32_e32 v247, v247, v132
	v_add_f32_e32 v247, v247, v133
	v_add_f32_e32 v247, v247, v134
	v_add_f32_e32 v247, v247, v135
	v_cvt_pk_bf16_f32 v178, v132, v133
	v_cvt_pk_bf16_f32 v179, v134, v135
	v_add_f32_e32 v247, v247, v136
	v_add_f32_e32 v247, v247, v137
	v_add_f32_e32 v247, v247, v138
	v_add_f32_e32 v247, v247, v139
	v_cvt_pk_bf16_f32 v180, v136, v137
	v_cvt_pk_bf16_f32 v181, v138, v139
	v_add_f32_e32 v247, v247, v140
	v_add_f32_e32 v247, v247, v141
	v_add_f32_e32 v247, v247, v142
	v_add_f32_e32 v247, v247, v143
	v_cvt_pk_bf16_f32 v182, v140, v141
	v_cvt_pk_bf16_f32 v183, v142, v143
	v_add_f32_e32 v247, v247, v144
	v_add_f32_e32 v247, v247, v145
	v_add_f32_e32 v247, v247, v146
	v_add_f32_e32 v247, v247, v147
	v_cvt_pk_bf16_f32 v184, v144, v145
	v_cvt_pk_bf16_f32 v185, v146, v147
	v_add_f32_e32 v247, v247, v148
	v_add_f32_e32 v247, v247, v149
	v_add_f32_e32 v247, v247, v150
	v_add_f32_e32 v247, v247, v151
	v_cvt_pk_bf16_f32 v186, v148, v149
	v_cvt_pk_bf16_f32 v187, v150, v151
	v_add_f32_e32 v247, v247, v152
	v_add_f32_e32 v247, v247, v153
	v_add_f32_e32 v247, v247, v154
	v_add_f32_e32 v247, v247, v155
	v_cvt_pk_bf16_f32 v188, v152, v153
	v_cvt_pk_bf16_f32 v189, v154, v155
	v_add_f32_e32 v247, v247, v156
	v_add_f32_e32 v247, v247, v157
	v_add_f32_e32 v247, v247, v158
	v_add_f32_e32 v247, v247, v159
	v_cvt_pk_bf16_f32 v190, v156, v157
	v_cvt_pk_bf16_f32 v191, v158, v159
	s_lshl_b32 s60, s56, 1
	v_add_u32_e32 v250, s60, v245
	ds_read_b64_tr_b16 v[192:193], v250 offset:0
	ds_read_b64_tr_b16 v[194:195], v250 offset:512
	ds_read_b64_tr_b16 v[196:197], v250 offset:4096
	ds_read_b64_tr_b16 v[198:199], v250 offset:4608
	ds_read_b64_tr_b16 v[200:201], v250 offset:8192
	ds_read_b64_tr_b16 v[202:203], v250 offset:8704
	ds_read_b64_tr_b16 v[204:205], v250 offset:12288
	ds_read_b64_tr_b16 v[206:207], v250 offset:12800
	s_waitcnt lgkmcnt(6)
	v_mfma_f32_32x32x16_bf16 v[32:47], v[176:179], v[192:195], v[32:47]
	ds_read_b64_tr_b16 v[192:193], v250 offset:1024
	ds_read_b64_tr_b16 v[194:195], v250 offset:1536
	s_waitcnt lgkmcnt(6)
	v_mfma_f32_32x32x16_bf16 v[48:63], v[176:179], v[196:199], v[48:63]
	ds_read_b64_tr_b16 v[196:197], v250 offset:5120
	ds_read_b64_tr_b16 v[198:199], v250 offset:5632
	s_waitcnt lgkmcnt(6)
	v_mfma_f32_32x32x16_bf16 v[64:79], v[176:179], v[200:203], v[64:79]
	ds_read_b64_tr_b16 v[200:201], v250 offset:9216
	ds_read_b64_tr_b16 v[202:203], v250 offset:9728
	s_waitcnt lgkmcnt(6)
	v_mfma_f32_32x32x16_bf16 v[80:95], v[176:179], v[204:207], v[80:95]
	ds_read_b64_tr_b16 v[204:205], v250 offset:13312
	ds_read_b64_tr_b16 v[206:207], v250 offset:13824
	s_waitcnt lgkmcnt(6)
	v_mfma_f32_32x32x16_bf16 v[32:47], v[180:183], v[192:195], v[32:47]
	ds_read_b64_tr_b16 v[192:193], v250 offset:2048
	ds_read_b64_tr_b16 v[194:195], v250 offset:2560
	s_waitcnt lgkmcnt(6)
	v_mfma_f32_32x32x16_bf16 v[48:63], v[180:183], v[196:199], v[48:63]
	ds_read_b64_tr_b16 v[196:197], v250 offset:6144
	ds_read_b64_tr_b16 v[198:199], v250 offset:6656
	s_waitcnt lgkmcnt(6)
	v_mfma_f32_32x32x16_bf16 v[64:79], v[180:183], v[200:203], v[64:79]
	ds_read_b64_tr_b16 v[200:201], v250 offset:10240
	ds_read_b64_tr_b16 v[202:203], v250 offset:10752
	s_waitcnt lgkmcnt(6)
	v_mfma_f32_32x32x16_bf16 v[80:95], v[180:183], v[204:207], v[80:95]
	ds_read_b64_tr_b16 v[204:205], v250 offset:14336
	ds_read_b64_tr_b16 v[206:207], v250 offset:14848
	s_waitcnt lgkmcnt(6)
	v_mfma_f32_32x32x16_bf16 v[32:47], v[184:187], v[192:195], v[32:47]
	ds_read_b64_tr_b16 v[192:193], v250 offset:3072
	ds_read_b64_tr_b16 v[194:195], v250 offset:3584
	s_waitcnt lgkmcnt(6)
	v_mfma_f32_32x32x16_bf16 v[48:63], v[184:187], v[196:199], v[48:63]
	ds_read_b64_tr_b16 v[196:197], v250 offset:7168
	ds_read_b64_tr_b16 v[198:199], v250 offset:7680
	s_waitcnt lgkmcnt(6)
	v_mfma_f32_32x32x16_bf16 v[64:79], v[184:187], v[200:203], v[64:79]
	ds_read_b64_tr_b16 v[200:201], v250 offset:11264
	ds_read_b64_tr_b16 v[202:203], v250 offset:11776
	s_waitcnt lgkmcnt(6)
	v_mfma_f32_32x32x16_bf16 v[80:95], v[184:187], v[204:207], v[80:95]
	ds_read_b64_tr_b16 v[204:205], v250 offset:15360
	ds_read_b64_tr_b16 v[206:207], v250 offset:15872
	s_waitcnt lgkmcnt(6)
	v_mfma_f32_32x32x16_bf16 v[32:47], v[188:191], v[192:195], v[32:47]
	s_waitcnt lgkmcnt(4)
	v_mfma_f32_32x32x16_bf16 v[48:63], v[188:191], v[196:199], v[48:63]
	s_waitcnt lgkmcnt(2)
	v_mfma_f32_32x32x16_bf16 v[64:79], v[188:191], v[200:203], v[64:79]
	s_waitcnt lgkmcnt(0)
	v_mfma_f32_32x32x16_bf16 v[80:95], v[188:191], v[204:207], v[80:95]
.Lat_epi:
	v_mov_b32_e32 v250, v247
	v_mov_b32_e32 v251, v247
	s_nop 1
	v_permlane32_swap_b32_e32 v250, v251
	v_add_f32_e32 v250, v250, v251
	s_waitcnt vmcnt(0) lgkmcnt(0)
	s_barrier
	v_and_b32_e32 v244, 31, v237
	v_lshl_add_u32 v244, v244, 2, v249
	v_cmp_eq_u32_e32 vcc, 0, v252
	s_and_saveexec_b64 s[60:61], vcc
	ds_write_b32 v244, v250 offset:128
	s_or_b64 exec, exec, s[60:61]
	s_waitcnt lgkmcnt(0)
	v_lshl_add_u32 v250, v252, 4, v249
	ds_read_b128 v[0:3], v250 offset:128
	ds_read_b128 v[4:7], v250 offset:160
	ds_read_b128 v[8:11], v250 offset:192
	ds_read_b128 v[12:15], v250 offset:224
	s_waitcnt lgkmcnt(0)
	v_rcp_f32_e32 v0, v0
	v_rcp_f32_e32 v1, v1
	v_rcp_f32_e32 v2, v2
	v_rcp_f32_e32 v3, v3
	v_rcp_f32_e32 v4, v4
	v_rcp_f32_e32 v5, v5
	v_rcp_f32_e32 v6, v6
	v_rcp_f32_e32 v7, v7
	v_rcp_f32_e32 v8, v8
	v_rcp_f32_e32 v9, v9
	v_rcp_f32_e32 v10, v10
	v_rcp_f32_e32 v11, v11
	v_rcp_f32_e32 v12, v12
	v_rcp_f32_e32 v13, v13
	v_rcp_f32_e32 v14, v14
	v_rcp_f32_e32 v15, v15
	s_nop 7
	s_nop 7
	s_lshl_b32 s60, s47, 13
	v_and_b32_e32 v250, 31, v237
	v_lshlrev_b32_e32 v250, 1, v250
	v_add_u32_e32 v250, s60, v250
	v_lshlrev_b32_e32 v251, 10, v252
	v_add_u32_e32 v250, v250, v251
	v_mul_f32_e32 v251, v32, v0
	v_cvt_pk_bf16_f32 v251, v251, v251
	ds_write_b16 v250, v251 offset:0
	v_mul_f32_e32 v251, v48, v0
	v_cvt_pk_bf16_f32 v251, v251, v251
	ds_write_b16 v250, v251 offset:64
	v_mul_f32_e32 v251, v64, v0
	v_cvt_pk_bf16_f32 v251, v251, v251
	ds_write_b16 v250, v251 offset:128
	v_mul_f32_e32 v251, v80, v0
	v_cvt_pk_bf16_f32 v251, v251, v251
	ds_write_b16 v250, v251 offset:192
	v_mul_f32_e32 v251, v33, v1
	v_cvt_pk_bf16_f32 v251, v251, v251
	ds_write_b16 v250, v251 offset:256
	v_mul_f32_e32 v251, v49, v1
	v_cvt_pk_bf16_f32 v251, v251, v251
	ds_write_b16 v250, v251 offset:320
	v_mul_f32_e32 v251, v65, v1
	v_cvt_pk_bf16_f32 v251, v251, v251
	ds_write_b16 v250, v251 offset:384
	v_mul_f32_e32 v251, v81, v1
	v_cvt_pk_bf16_f32 v251, v251, v251
	ds_write_b16 v250, v251 offset:448
	v_mul_f32_e32 v251, v34, v2
	v_cvt_pk_bf16_f32 v251, v251, v251
	ds_write_b16 v250, v251 offset:512
	v_mul_f32_e32 v251, v50, v2
	v_cvt_pk_bf16_f32 v251, v251, v251
	ds_write_b16 v250, v251 offset:576
	v_mul_f32_e32 v251, v66, v2
	v_cvt_pk_bf16_f32 v251, v251, v251
	ds_write_b16 v250, v251 offset:640
	v_mul_f32_e32 v251, v82, v2
	v_cvt_pk_bf16_f32 v251, v251, v251
	ds_write_b16 v250, v251 offset:704
	v_mul_f32_e32 v251, v35, v3
	v_cvt_pk_bf16_f32 v251, v251, v251
	ds_write_b16 v250, v251 offset:768
	v_mul_f32_e32 v251, v51, v3
	v_cvt_pk_bf16_f32 v251, v251, v251
	ds_write_b16 v250, v251 offset:832
	v_mul_f32_e32 v251, v67, v3
	v_cvt_pk_bf16_f32 v251, v251, v251
	ds_write_b16 v250, v251 offset:896
	v_mul_f32_e32 v251, v83, v3
	v_cvt_pk_bf16_f32 v251, v251, v251
	ds_write_b16 v250, v251 offset:960
	v_mul_f32_e32 v251, v36, v4
	v_cvt_pk_bf16_f32 v251, v251, v251
	ds_write_b16 v250, v251 offset:2048
	v_mul_f32_e32 v251, v52, v4
	v_cvt_pk_bf16_f32 v251, v251, v251
	ds_write_b16 v250, v251 offset:2112
	v_mul_f32_e32 v251, v68, v4
	v_cvt_pk_bf16_f32 v251, v251, v251
	ds_write_b16 v250, v251 offset:2176
	v_mul_f32_e32 v251, v84, v4
	v_cvt_pk_bf16_f32 v251, v251, v251
	ds_write_b16 v250, v251 offset:2240
	v_mul_f32_e32 v251, v37, v5
	v_cvt_pk_bf16_f32 v251, v251, v251
	ds_write_b16 v250, v251 offset:2304
	v_mul_f32_e32 v251, v53, v5
	v_cvt_pk_bf16_f32 v251, v251, v251
	ds_write_b16 v250, v251 offset:2368
	v_mul_f32_e32 v251, v69, v5
	v_cvt_pk_bf16_f32 v251, v251, v251
	ds_write_b16 v250, v251 offset:2432
	v_mul_f32_e32 v251, v85, v5
	v_cvt_pk_bf16_f32 v251, v251, v251
	ds_write_b16 v250, v251 offset:2496
	v_mul_f32_e32 v251, v38, v6
	v_cvt_pk_bf16_f32 v251, v251, v251
	ds_write_b16 v250, v251 offset:2560
	v_mul_f32_e32 v251, v54, v6
	v_cvt_pk_bf16_f32 v251, v251, v251
	ds_write_b16 v250, v251 offset:2624
	v_mul_f32_e32 v251, v70, v6
	v_cvt_pk_bf16_f32 v251, v251, v251
	ds_write_b16 v250, v251 offset:2688
	v_mul_f32_e32 v251, v86, v6
	v_cvt_pk_bf16_f32 v251, v251, v251
	ds_write_b16 v250, v251 offset:2752
	v_mul_f32_e32 v251, v39, v7
	v_cvt_pk_bf16_f32 v251, v251, v251
	ds_write_b16 v250, v251 offset:2816
	v_mul_f32_e32 v251, v55, v7
	v_cvt_pk_bf16_f32 v251, v251, v251
	ds_write_b16 v250, v251 offset:2880
	v_mul_f32_e32 v251, v71, v7
	v_cvt_pk_bf16_f32 v251, v251, v251
	ds_write_b16 v250, v251 offset:2944
	v_mul_f32_e32 v251, v87, v7
	v_cvt_pk_bf16_f32 v251, v251, v251
	ds_write_b16 v250, v251 offset:3008
	v_mul_f32_e32 v251, v40, v8
	v_cvt_pk_bf16_f32 v251, v251, v251
	ds_write_b16 v250, v251 offset:4096
	v_mul_f32_e32 v251, v56, v8
	v_cvt_pk_bf16_f32 v251, v251, v251
	ds_write_b16 v250, v251 offset:4160
	v_mul_f32_e32 v251, v72, v8
	v_cvt_pk_bf16_f32 v251, v251, v251
	ds_write_b16 v250, v251 offset:4224
	v_mul_f32_e32 v251, v88, v8
	v_cvt_pk_bf16_f32 v251, v251, v251
	ds_write_b16 v250, v251 offset:4288
	v_mul_f32_e32 v251, v41, v9
	v_cvt_pk_bf16_f32 v251, v251, v251
	ds_write_b16 v250, v251 offset:4352
	v_mul_f32_e32 v251, v57, v9
	v_cvt_pk_bf16_f32 v251, v251, v251
	ds_write_b16 v250, v251 offset:4416
	v_mul_f32_e32 v251, v73, v9
	v_cvt_pk_bf16_f32 v251, v251, v251
	ds_write_b16 v250, v251 offset:4480
	v_mul_f32_e32 v251, v89, v9
	v_cvt_pk_bf16_f32 v251, v251, v251
	ds_write_b16 v250, v251 offset:4544
	v_mul_f32_e32 v251, v42, v10
	v_cvt_pk_bf16_f32 v251, v251, v251
	ds_write_b16 v250, v251 offset:4608
	v_mul_f32_e32 v251, v58, v10
	v_cvt_pk_bf16_f32 v251, v251, v251
	ds_write_b16 v250, v251 offset:4672
	v_mul_f32_e32 v251, v74, v10
	v_cvt_pk_bf16_f32 v251, v251, v251
	ds_write_b16 v250, v251 offset:4736
	v_mul_f32_e32 v251, v90, v10
	v_cvt_pk_bf16_f32 v251, v251, v251
	ds_write_b16 v250, v251 offset:4800
	v_mul_f32_e32 v251, v43, v11
	v_cvt_pk_bf16_f32 v251, v251, v251
	ds_write_b16 v250, v251 offset:4864
	v_mul_f32_e32 v251, v59, v11
	v_cvt_pk_bf16_f32 v251, v251, v251
	ds_write_b16 v250, v251 offset:4928
	v_mul_f32_e32 v251, v75, v11
	v_cvt_pk_bf16_f32 v251, v251, v251
	ds_write_b16 v250, v251 offset:4992
	v_mul_f32_e32 v251, v91, v11
	v_cvt_pk_bf16_f32 v251, v251, v251
	ds_write_b16 v250, v251 offset:5056
	v_mul_f32_e32 v251, v44, v12
	v_cvt_pk_bf16_f32 v251, v251, v251
	ds_write_b16 v250, v251 offset:6144
	v_mul_f32_e32 v251, v60, v12
	v_cvt_pk_bf16_f32 v251, v251, v251
	ds_write_b16 v250, v251 offset:6208
	v_mul_f32_e32 v251, v76, v12
	v_cvt_pk_bf16_f32 v251, v251, v251
	ds_write_b16 v250, v251 offset:6272
	v_mul_f32_e32 v251, v92, v12
	v_cvt_pk_bf16_f32 v251, v251, v251
	ds_write_b16 v250, v251 offset:6336
	v_mul_f32_e32 v251, v45, v13
	v_cvt_pk_bf16_f32 v251, v251, v251
	ds_write_b16 v250, v251 offset:6400
	v_mul_f32_e32 v251, v61, v13
	v_cvt_pk_bf16_f32 v251, v251, v251
	ds_write_b16 v250, v251 offset:6464
	v_mul_f32_e32 v251, v77, v13
	v_cvt_pk_bf16_f32 v251, v251, v251
	ds_write_b16 v250, v251 offset:6528
	v_mul_f32_e32 v251, v93, v13
	v_cvt_pk_bf16_f32 v251, v251, v251
	ds_write_b16 v250, v251 offset:6592
	v_mul_f32_e32 v251, v46, v14
	v_cvt_pk_bf16_f32 v251, v251, v251
	ds_write_b16 v250, v251 offset:6656
	v_mul_f32_e32 v251, v62, v14
	v_cvt_pk_bf16_f32 v251, v251, v251
	ds_write_b16 v250, v251 offset:6720
	v_mul_f32_e32 v251, v78, v14
	v_cvt_pk_bf16_f32 v251, v251, v251
	ds_write_b16 v250, v251 offset:6784
	v_mul_f32_e32 v251, v94, v14
	v_cvt_pk_bf16_f32 v251, v251, v251
	ds_write_b16 v250, v251 offset:6848
	v_mul_f32_e32 v251, v47, v15
	v_cvt_pk_bf16_f32 v251, v251, v251
	ds_write_b16 v250, v251 offset:6912
	v_mul_f32_e32 v251, v63, v15
	v_cvt_pk_bf16_f32 v251, v251, v251
	ds_write_b16 v250, v251 offset:6976
	v_mul_f32_e32 v251, v79, v15
	v_cvt_pk_bf16_f32 v251, v251, v251
	ds_write_b16 v250, v251 offset:7040
	v_mul_f32_e32 v251, v95, v15
	v_cvt_pk_bf16_f32 v251, v251, v251
	ds_write_b16 v250, v251 offset:7104
	s_waitcnt lgkmcnt(0)
	v_lshrrev_b32_e32 v251, 4, v237
	v_and_b32_e32 v244, 15, v237
	v_lshlrev_b32_e32 v245, 8, v251
	v_lshl_or_b32 v245, v244, 4, v245
	v_add_u32_e32 v245, s60, v245
	v_lshlrev_b32_e32 v246, 11, v251
	v_lshl_or_b32 v246, v244, 4, v246
	ds_read_b128 v[16:19], v245 offset:0
	s_waitcnt lgkmcnt(0)
	global_store_dwordx4 v246, v[16:19], s[52:53]
	v_add_u32_e32 v246, 0x2000, v246
	s_nop 1
	ds_read_b128 v[16:19], v245 offset:1024
	s_waitcnt lgkmcnt(0)
	global_store_dwordx4 v246, v[16:19], s[52:53]
	v_add_u32_e32 v246, 0x2000, v246
	s_nop 1
	ds_read_b128 v[16:19], v245 offset:2048
	s_waitcnt lgkmcnt(0)
	global_store_dwordx4 v246, v[16:19], s[52:53]
	v_add_u32_e32 v246, 0x2000, v246
	s_nop 1
	ds_read_b128 v[16:19], v245 offset:3072
	s_waitcnt lgkmcnt(0)
	global_store_dwordx4 v246, v[16:19], s[52:53]
	v_add_u32_e32 v246, 0x2000, v246
	s_nop 1
	ds_read_b128 v[16:19], v245 offset:4096
	s_waitcnt lgkmcnt(0)
	global_store_dwordx4 v246, v[16:19], s[52:53]
	v_add_u32_e32 v246, 0x2000, v246
	s_nop 1
	ds_read_b128 v[16:19], v245 offset:5120
	s_waitcnt lgkmcnt(0)
	global_store_dwordx4 v246, v[16:19], s[52:53]
	v_add_u32_e32 v246, 0x2000, v246
	s_nop 1
	ds_read_b128 v[16:19], v245 offset:6144
	s_waitcnt lgkmcnt(0)
	global_store_dwordx4 v246, v[16:19], s[52:53]
	v_add_u32_e32 v246, 0x2000, v246
	s_nop 1
	ds_read_b128 v[16:19], v245 offset:7168
	s_waitcnt lgkmcnt(0)
	global_store_dwordx4 v246, v[16:19], s[52:53]
	v_add_u32_e32 v246, 0x2000, v246
	s_nop 1
	s_waitcnt lgkmcnt(0)
	s_barrier
